# GU/IN: consecutive units with the same row tile reuse the LDS rstd table (no rss reload / re-reduction); vmcnt count per case
# speedup vs baseline: 1.0077x; 1.0025x over previous
; DI float rss_sum(const float* rss, int row) {
;     const f32x4* p = (const f32x4*)(rss + (size_t)row * 16); const f32x4 a = p[0], b = p[1], c = p[2], d = p[3];
;     return (((a.x + a.y) + (a.z + a.w)) + ((b.x + b.y) + (b.z + b.w))) + (((c.x + c.y) + (c.z + c.w)) + ((d.x + d.y) + (d.z + d.w))); }
; DI void row_rstd8(const float* rss, int row0, int lane, int fq, float (&rs)[8]) {
;     float v[2];
; #pragma unroll
;     for (int e = 0; e < 2; ++e) { const int p = 2 * fq + e; const int row = row0 + (p >> 2) * 128 + (p & 3) * 16; v[e] = 1.0f / sqrtf(rss_sum(rss, row) * (1.0f / DM) + EPS); }
;     const int fr = lane & 15;
; #pragma unroll
;     for (int q = 0; q < 4; ++q) { rs[2 * q] = __shfl(v[0], fr + 16 * q); rs[2 * q + 1] = __shfl(v[1], fr + 16 * q); }
.LBB0_419:
	s_cmp_lg_u32 s72, 1
	s_cbranch_scc1 .Lin_nf
	s_mov_b32 s100, 0
	s_mov_b32 s101, 1
	v_readlane_b32 s26, v253, 49
	s_lshl_b32 s27, s6, 14
	s_nop 1
	s_add_u32 s26, s26, s27
	v_readlane_b32 s27, v253, 50
	s_nop 1
	s_addc_u32 s27, s27, 0
	s_nop 4
	global_load_dwordx4 v[228:231], v252, s[26:27]
	global_load_dwordx2 v[232:233], v252, s[26:27] offset:16
	global_load_dwordx2 v[238:239], v252, s[26:27] offset:24
	s_branch .Lin_noR0
.Lin_nf:
	s_sub_u32 s100, 2, s101

; #define PG8_STAGE(bufoff, gbase, voff) do { _Pragma("unroll") for (int _i = 0; _i < 2; ++_i) \
;         __builtin_amdgcn_global_load_lds((const unsigned*)((const char*)(gbase) + (voff)[_i]), (LAS unsigned*)(lds + (bufoff) + ldsw + _i * 8192), 16, 0, 0); } while (0)
; #define PG8_LDA(dst, b, h) do { _Pragma("unroll") for (int m = 0; m < 4; ++m) _Pragma("unroll") for (int k = 0; k < 2; ++k) dst[m][k] = *(const LAS bf16x8*)(lds + PG8_SA(b, h) + aoff + m * 2048 + k * 1024); } while (0)
; #define PG8_LDB(dst, b, h) do { _Pragma("unroll") for (int n = 0; n < 2; ++n) _Pragma("unroll") for (int k = 0; k < 2; ++k) dst[n][k] = *(const LAS bf16x8*)(lds + PG8_SB(b, h) + boff + n * 2048 + k * 1024); } while (0)
; #define PG8_MMA(ai, bj, At, Bt) do { __builtin_amdgcn_s_setprio(1); _Pragma("unroll") for (int m = 0; m < 4; ++m) _Pragma("unroll") for (int n = 0; n < 2; ++n) _Pragma("unroll") for (int k = 0; k < 2; ++k) \
;         acc[ai][bj][m][n] = __builtin_amdgcn_mfma_f32_16x16x32_bf16(Bt[n][k], At[m][k], acc[ai][bj][m][n], 0, 0, 0); __builtin_amdgcn_s_setprio(0); } while (0)
; #define PG8_WAIT_V(n) asm volatile("s_waitcnt vmcnt(" #n ")" ::: "memory")
; #define PG8_WAIT_L(n) asm volatile("s_waitcnt lgkmcnt(" #n ")" ::: "memory")
; DI void row_rstd8(const float* rss, int row0, int lane, int fq, float (&rs)[8]) {
;     float v[2];
; #pragma unroll
;     for (int e = 0; e < 2; ++e) { const int p = 2 * fq + e; const int row = row0 + (p >> 2) * 128 + (p & 3) * 16; v[e] = 1.0f / sqrtf(rss_sum(rss, row) * (1.0f / DM) + EPS); }
;     const int fr = lane & 15;
; #pragma unroll
;     for (int q = 0; q < 4; ++q) { rs[2 * q] = __shfl(v[0], fr + 16 * q); rs[2 * q + 1] = __shfl(v[1], fr + 16 * q); }
; template <class Epi>
; DI void gemm_phase(LAS unsigned char* lds, const int tid, const Gemm g, const StaticOrder& S, const Epi& E) {
;     ...
;             PG8_LDB(B0, 0, 0); PG8_LDB(B1, 0, 1); PG8_SCHED; PG8_LDA(At, 0, 0); PG8_STAGE(PG8_SA(1, 1), a1 + hstepA, voffA);
;             PG8_WAIT_V(8); PG8_WAIT_L(0); PG8_BAR; PG8_MMA(0, 0, At, B0); PG8_MMA(0, 1, At, B1); PG8_BAR; PG8_SCHED;
;             PG8_LDA(At, 0, 1); PG8_STAGE(PG8_SB(0, 0), b2, voffB); PG8_STAGE(PG8_SB(0, 1), b2 + hstepB, voffB); PG8_STAGE(PG8_SA(0, 0), a2, voffA);
;             PG8_WAIT_V(8); PG8_WAIT_L(0); PG8_BAR; PG8_MMA(1, 0, At, B0); PG8_MMA(1, 1, At, B1); PG8_BAR; PG8_SCHED;
.LBB0_420:
	s_cmp_eq_u32 s82, 0
	s_cbranch_scc0 .Lin_rs_skip
	s_cmp_eq_u32 s101, 1
	s_cbranch_scc0 .Lin_rs_skip
	s_waitcnt vmcnt(8)
	v_add_f32_e32 v152, v228, v229
	v_add_f32_e32 v153, v230, v231
	v_add_f32_e32 v154, v232, v233
	v_add_f32_e32 v155, v238, v239
	v_add_f32_e32 v152, v152, v153
	v_add_f32_e32 v154, v154, v155
	v_add_f32_e32 v152, v152, v154
	s_nop 1
	v_mov_b32_dpp v153, v152 quad_perm:[1,0,3,2] row_mask:0xf bank_mask:0xf
	s_nop 0
	v_add_f32_e32 v152, v152, v153
	v_fmamk_f32 v152, v152, 0x3a800000, v241
	v_cmp_gt_f32_e32 vcc, s3, v152
	v_mul_f32_e32 v153, 0x4f800000, v152
	s_nop 1
	v_cndmask_b32_e32 v152, v152, v153, vcc
	v_sqrt_f32_e32 v153, v152
	s_nop 0
	v_add_u32_e32 v154, -1, v153
	v_fma_f32 v155, -v154, v153, v152
	v_cmp_ge_f32_e64 s[26:27], 0, v155
	v_add_u32_e32 v155, 1, v153
	s_nop 1
	v_cndmask_b32_e64 v154, v153, v154, s[26:27]
	v_fma_f32 v153, -v155, v153, v152
	v_cmp_lt_f32_e64 s[26:27], 0, v153
	s_nop 1
	v_cndmask_b32_e64 v153, v154, v155, s[26:27]
	v_mul_f32_e32 v154, 0x37800000, v153
	v_cndmask_b32_e32 v153, v153, v154, vcc
	v_cmp_class_f32_e32 vcc, v152, v242
	s_nop 1
	v_cndmask_b32_e32 v152, v153, v152, vcc
	v_div_scale_f32 v153, s[26:27], v152, v152, 1.0
	v_rcp_f32_e32 v154, v153
	s_nop 0
	v_fma_f32 v155, -v153, v154, 1.0
	v_fmac_f32_e32 v154, v155, v154
	v_div_scale_f32 v155, vcc, 1.0, v152, 1.0
	v_mul_f32_e32 v156, v155, v154
	v_fma_f32 v157, -v153, v156, v155
	v_fmac_f32_e32 v156, v157, v154
	v_fma_f32 v153, -v153, v156, v155
	s_nop 0
	v_div_fmas_f32 v153, v153, v154, v156
	v_div_fixup_f32 v152, v153, v152, 1.0
	ds_write_b32 v251, v152
.Lin_rs_skip:
	s_add_u32 s26, s58, 0xfffc0080
	s_addc_u32 s27, s59, -1
	s_add_i32 s83, 0, 0x10000
	s_cmp_eq_u32 s82, 12
	s_cselect_b32 s63, s49, s27
	s_cselect_b32 s62, s78, s26
	v_add_u32_e32 v144, s83, v147
	s_cselect_b32 s61, s37, s81
	s_cselect_b32 s60, s79, s80
	s_add_i32 s84, 0, 0x14000
	ds_read_b128 v[140:143], v144
	ds_read_b128 v[152:155], v144 offset:1024
	ds_read_b128 v[156:159], v144 offset:2048
	ds_read_b128 v[160:163], v144 offset:3072
	v_add_u32_e32 v144, s84, v147
	ds_read_b128 v[164:167], v144
	ds_read_b128 v[168:171], v144 offset:1024
	ds_read_b128 v[172:175], v144 offset:2048
	ds_read_b128 v[176:179], v144 offset:3072
	v_lshl_add_u64 v[204:205], s[58:59], 0, v[136:137]
	s_add_i32 m0, s42, 0xc000
	ds_read_b128 v[180:183], v150
	ds_read_b128 v[184:187], v150 offset:1024
	ds_read_b128 v[188:191], v150 offset:2048
	ds_read_b128 v[192:195], v150 offset:3072
	ds_read_b128 v[196:199], v150 offset:4096
	ds_read_b128 v[200:203], v150 offset:5120
	ds_read_b128 v[208:211], v150 offset:6144
	ds_read_b128 v[212:215], v150 offset:7168
	global_load_lds_dwordx4 v[204:205], off
	v_lshl_add_u64 v[204:205], s[58:59], 0, v[138:139]
	s_add_i32 m0, s42, 0xe000
	s_nop 0
	global_load_lds_dwordx4 v[204:205], off
	s_cmp_eq_u32 s100, 0
	s_cbranch_scc1 .Lin_ws1
	s_cmp_eq_u32 s100, 1
	s_cbranch_scc1 .Lin_wr1
	s_waitcnt vmcnt(24)
	s_branch .Lin_wq1
.Lin_wr1:
	s_waitcnt vmcnt(27)
.Lin_wq1:
	s_branch .Lin_wd1
.Lin_ws1:
	s_waitcnt vmcnt(8)
.Lin_wd1:
	s_waitcnt lgkmcnt(0)
	s_barrier
	s_setprio 1
	s_waitcnt lgkmcnt(0)
	v_mfma_f32_16x16x32_bf16 v[126:129], v[140:143], v[180:183], v[126:129]
	v_mfma_f32_16x16x32_bf16 v[122:125], v[156:159], v[180:183], v[122:125]
	v_mfma_f32_16x16x32_bf16 v[118:121], v[140:143], v[188:191], v[118:121]
	v_mfma_f32_16x16x32_bf16 v[110:113], v[156:159], v[188:191], v[110:113]
	v_mfma_f32_16x16x32_bf16 v[102:105], v[140:143], v[196:199], v[102:105]
	v_mfma_f32_16x16x32_bf16 v[94:97], v[156:159], v[196:199], v[94:97]
	v_mfma_f32_16x16x32_bf16 v[86:89], v[140:143], v[208:211], v[86:89]
	v_mfma_f32_16x16x32_bf16 v[78:81], v[156:159], v[208:211], v[78:81]
	v_mfma_f32_16x16x32_bf16 v[126:129], v[152:155], v[184:187], v[126:129]
	v_mfma_f32_16x16x32_bf16 v[122:125], v[160:163], v[184:187], v[122:125]
	v_mfma_f32_16x16x32_bf16 v[118:121], v[152:155], v[192:195], v[118:121]
	v_mfma_f32_16x16x32_bf16 v[110:113], v[160:163], v[192:195], v[110:113]
	v_mfma_f32_16x16x32_bf16 v[102:105], v[152:155], v[200:203], v[102:105]
	v_mfma_f32_16x16x32_bf16 v[94:97], v[160:163], v[200:203], v[94:97]
	v_mfma_f32_16x16x32_bf16 v[86:89], v[152:155], v[212:215], v[86:89]
	v_mfma_f32_16x16x32_bf16 v[78:81], v[160:163], v[212:215], v[78:81]
	s_setprio 0
	s_setprio 1
	v_mfma_f32_16x16x32_bf16 v[114:117], v[164:167], v[180:183], v[114:117]
	v_mfma_f32_16x16x32_bf16 v[106:109], v[172:175], v[180:183], v[106:109]
	v_mfma_f32_16x16x32_bf16 v[98:101], v[164:167], v[188:191], v[98:101]
	v_mfma_f32_16x16x32_bf16 v[90:93], v[172:175], v[188:191], v[90:93]
	v_mfma_f32_16x16x32_bf16 v[82:85], v[164:167], v[196:199], v[82:85]
	v_mfma_f32_16x16x32_bf16 v[74:77], v[172:175], v[196:199], v[74:77]
	v_mfma_f32_16x16x32_bf16 v[70:73], v[164:167], v[208:211], v[70:73]
	v_mfma_f32_16x16x32_bf16 v[66:69], v[172:175], v[208:211], v[66:69]
	v_mfma_f32_16x16x32_bf16 v[114:117], v[168:171], v[184:187], v[114:117]
	v_mfma_f32_16x16x32_bf16 v[106:109], v[176:179], v[184:187], v[106:109]
	v_mfma_f32_16x16x32_bf16 v[98:101], v[168:171], v[192:195], v[98:101]
	v_mfma_f32_16x16x32_bf16 v[90:93], v[176:179], v[192:195], v[90:93]
	v_mfma_f32_16x16x32_bf16 v[82:85], v[168:171], v[200:203], v[82:85]
	v_mfma_f32_16x16x32_bf16 v[74:77], v[176:179], v[200:203], v[74:77]
	v_mfma_f32_16x16x32_bf16 v[70:73], v[168:171], v[212:215], v[70:73]
	v_mfma_f32_16x16x32_bf16 v[66:69], v[176:179], v[212:215], v[66:69]
	s_setprio 0
	s_barrier
	s_add_i32 s26, s83, s30
	v_lshl_add_u64 v[204:205], s[60:61], 0, v[0:1]
	s_mov_b32 m0, s26
	ds_read_b128 v[180:183], v150 offset:16384
	ds_read_b128 v[184:187], v150 offset:17408
	ds_read_b128 v[188:191], v150 offset:18432
	ds_read_b128 v[192:195], v150 offset:19456
	ds_read_b128 v[196:199], v150 offset:20480
	ds_read_b128 v[200:203], v150 offset:21504
	ds_read_b128 v[208:211], v150 offset:22528
	ds_read_b128 v[212:215], v150 offset:23552
	global_load_lds_dwordx4 v[204:205], off
	s_add_i32 m0, s26, 0x2000
	s_add_u32 s26, s60, 0x40000
	v_lshl_add_u64 v[216:217], s[60:61], 0, v[130:131]
	s_addc_u32 s27, s61, 0
	s_add_i32 s83, s84, s30
	global_load_lds_dwordx4 v[216:217], off
	v_lshl_add_u64 v[218:219], s[26:27], 0, v[0:1]
	s_mov_b32 m0, s83
	v_lshl_add_u64 v[220:221], s[62:63], 0, v[132:133]
	global_load_lds_dwordx4 v[218:219], off
	v_lshl_add_u64 v[218:219], s[26:27], 0, v[130:131]
	s_add_i32 m0, s83, 0x2000
	s_nop 0
	global_load_lds_dwordx4 v[218:219], off
	v_lshl_add_u64 v[218:219], s[62:63], 0, v[134:135]
	s_mov_b32 m0, s42
	s_nop 0
	global_load_lds_dwordx4 v[218:219], off
	s_mov_b32 m0, s43
	s_nop 0
	global_load_lds_dwordx4 v[220:221], off
	s_cmp_eq_u32 s100, 0
	s_cbranch_scc1 .Lin_ws2
	s_cmp_eq_u32 s100, 1
	s_cbranch_scc1 .Lin_wr2
	s_waitcnt vmcnt(24)
	s_branch .Lin_wq2

; #define PG8_STAGE(bufoff, gbase, voff) do { _Pragma("unroll") for (int _i = 0; _i < 2; ++_i) \
;         __builtin_amdgcn_global_load_lds((const unsigned*)((const char*)(gbase) + (voff)[_i]), (LAS unsigned*)(lds + (bufoff) + ldsw + _i * 8192), 16, 0, 0); } while (0)
; #define PG8_LDA(dst, b, h) do { _Pragma("unroll") for (int m = 0; m < 4; ++m) _Pragma("unroll") for (int k = 0; k < 2; ++k) dst[m][k] = *(const LAS bf16x8*)(lds + PG8_SA(b, h) + aoff + m * 2048 + k * 1024); } while (0)
; #define PG8_LDB(dst, b, h) do { _Pragma("unroll") for (int n = 0; n < 2; ++n) _Pragma("unroll") for (int k = 0; k < 2; ++k) dst[n][k] = *(const LAS bf16x8*)(lds + PG8_SB(b, h) + boff + n * 2048 + k * 1024); } while (0)
; #define PG8_MMA(ai, bj, At, Bt) do { __builtin_amdgcn_s_setprio(1); _Pragma("unroll") for (int m = 0; m < 4; ++m) _Pragma("unroll") for (int n = 0; n < 2; ++n) _Pragma("unroll") for (int k = 0; k < 2; ++k) \
;         acc[ai][bj][m][n] = __builtin_amdgcn_mfma_f32_16x16x32_bf16(Bt[n][k], At[m][k], acc[ai][bj][m][n], 0, 0, 0); __builtin_amdgcn_s_setprio(0); } while (0)
; #define PG8_WAIT_V(n) asm volatile("s_waitcnt vmcnt(" #n ")" ::: "memory")
; #define PG8_WAIT_L(n) asm volatile("s_waitcnt lgkmcnt(" #n ")" ::: "memory")
; #define PG8_BAR __builtin_amdgcn_s_barrier()
; #define PG8_SCHED __builtin_amdgcn_sched_barrier(0)
; template <class Epi>
; DI void gemm_phase(LAS unsigned char* lds, const int tid, const Gemm g, const StaticOrder& S, const Epi& E) {
;     ...
;             PG8_LDB(B0, 0, 0); PG8_LDB(B1, 0, 1); PG8_SCHED; PG8_LDA(At, 0, 0); PG8_STAGE(PG8_SA(1, 1), a1 + hstepA, voffA);
;             PG8_WAIT_V(8); PG8_WAIT_L(0); PG8_BAR; PG8_MMA(0, 0, At, B0); PG8_MMA(0, 1, At, B1); PG8_BAR; PG8_SCHED;
;             PG8_LDA(At, 0, 1); PG8_STAGE(PG8_SB(0, 0), b2, voffB); PG8_STAGE(PG8_SB(0, 1), b2 + hstepB, voffB); PG8_STAGE(PG8_SA(0, 0), a2, voffA);
;             PG8_WAIT_V(8); PG8_WAIT_L(0); PG8_BAR; PG8_MMA(1, 0, At, B0); PG8_MMA(1, 1, At, B1); PG8_BAR; PG8_SCHED;
.Lin_wq2:
	s_mov_b32 s100, 0
	s_branch .Lin_wd2

; DI float rss_sum(const float* rss, int row) {
;     const f32x4* p = (const f32x4*)(rss + (size_t)row * 16); const f32x4 a = p[0], b = p[1], c = p[2], d = p[3];
;     return (((a.x + a.y) + (a.z + a.w)) + ((b.x + b.y) + (b.z + b.w))) + (((c.x + c.y) + (c.z + c.w)) + ((d.x + d.y) + (d.z + d.w))); }
; DI void row_rstd8(const float* rss, int row0, int lane, int fq, float (&rs)[8]) {
;     float v[2];
; #pragma unroll
;     for (int e = 0; e < 2; ++e) { const int p = 2 * fq + e; const int row = row0 + (p >> 2) * 128 + (p & 3) * 16; v[e] = 1.0f / sqrtf(rss_sum(rss, row) * (1.0f / DM) + EPS); }
; template <class Epi>
; DI void gemm_phase(LAS unsigned char* lds, const int tid, const Gemm g, const StaticOrder& S, const Epi& E) {
;     ...
;         const bool has_next = S.next(ui + 1, nxt);
;         const char* nA = has_next ? (const char*)g.A + (size_t)nxt.pm * tstepA : cA; const char* nB = has_next ? (const char*)g.Bt + (size_t)nxt.pn * tstepB : cB;
.LBB0_423:
	s_mov_b32 s101, 0
	s_andn2_b64 vcc, exec, s[4:5]
	s_cbranch_vccnz .Lin_noR
	s_cmp_eq_u32 s48, s6
	s_cbranch_scc1 .Lin_noR
	s_mov_b32 s101, 1
	v_readlane_b32 s0, v253, 49
	s_and_b32 s1, s48, 0x7f
	s_lshl_b32 s1, s1, 14
	s_nop 0
	s_add_u32 s0, s0, s1
	v_readlane_b32 s1, v253, 50
	s_nop 1
	s_addc_u32 s1, s1, 0
	s_nop 4
	global_load_dwordx4 v[228:231], v252, s[0:1]
	global_load_dwordx2 v[232:233], v252, s[0:1] offset:16
	global_load_dwordx2 v[238:239], v252, s[0:1] offset:24

; DI float rss_sum(const float* rss, int row) {
;     const f32x4* p = (const f32x4*)(rss + (size_t)row * 16); const f32x4 a = p[0], b = p[1], c = p[2], d = p[3];
;     return (((a.x + a.y) + (a.z + a.w)) + ((b.x + b.y) + (b.z + b.w))) + (((c.x + c.y) + (c.z + c.w)) + ((d.x + d.y) + (d.z + d.w))); }
; DI void row_rstd8(const float* rss, int row0, int lane, int fq, float (&rs)[8]) {
;     float v[2];
; #pragma unroll
;     for (int e = 0; e < 2; ++e) { const int p = 2 * fq + e; const int row = row0 + (p >> 2) * 128 + (p & 3) * 16; v[e] = 1.0f / sqrtf(rss_sum(rss, row) * (1.0f / DM) + EPS); }
;     const int fr = lane & 15;
; #pragma unroll
;     for (int q = 0; q < 4; ++q) { rs[2 * q] = __shfl(v[0], fr + 16 * q); rs[2 * q + 1] = __shfl(v[1], fr + 16 * q); }
.LBB0_666:
	s_cmp_lg_u32 s46, 1
	s_cbranch_scc1 .Lgu_nf
	s_mov_b32 s100, 0
	s_mov_b32 s101, 1
	v_readlane_b32 s26, v253, 49
	s_lshl_b32 s27, s49, 14
	s_nop 1
	s_add_u32 s26, s26, s27
	v_readlane_b32 s27, v253, 50
	s_nop 1
	s_addc_u32 s27, s27, 0
	s_nop 4
	global_load_dwordx4 v[228:231], v252, s[26:27]
	global_load_dwordx2 v[232:233], v252, s[26:27] offset:16
	global_load_dwordx2 v[238:239], v252, s[26:27] offset:24
	s_branch .Lgu_noR0

; #define PG8_STAGE(bufoff, gbase, voff) do { _Pragma("unroll") for (int _i = 0; _i < 2; ++_i) \
;         __builtin_amdgcn_global_load_lds((const unsigned*)((const char*)(gbase) + (voff)[_i]), (LAS unsigned*)(lds + (bufoff) + ldsw + _i * 8192), 16, 0, 0); } while (0)
; #define PG8_LDA(dst, b, h) do { _Pragma("unroll") for (int m = 0; m < 4; ++m) _Pragma("unroll") for (int k = 0; k < 2; ++k) dst[m][k] = *(const LAS bf16x8*)(lds + PG8_SA(b, h) + aoff + m * 2048 + k * 1024); } while (0)
; #define PG8_LDB(dst, b, h) do { _Pragma("unroll") for (int n = 0; n < 2; ++n) _Pragma("unroll") for (int k = 0; k < 2; ++k) dst[n][k] = *(const LAS bf16x8*)(lds + PG8_SB(b, h) + boff + n * 2048 + k * 1024); } while (0)
; #define PG8_MMA(ai, bj, At, Bt) do { __builtin_amdgcn_s_setprio(1); _Pragma("unroll") for (int m = 0; m < 4; ++m) _Pragma("unroll") for (int n = 0; n < 2; ++n) _Pragma("unroll") for (int k = 0; k < 2; ++k) \
;         acc[ai][bj][m][n] = __builtin_amdgcn_mfma_f32_16x16x32_bf16(Bt[n][k], At[m][k], acc[ai][bj][m][n], 0, 0, 0); __builtin_amdgcn_s_setprio(0); } while (0)
; #define PG8_WAIT_V(n) asm volatile("s_waitcnt vmcnt(" #n ")" ::: "memory")
; #define PG8_WAIT_L(n) asm volatile("s_waitcnt lgkmcnt(" #n ")" ::: "memory")
; DI void row_rstd8(const float* rss, int row0, int lane, int fq, float (&rs)[8]) {
;     float v[2];
; #pragma unroll
;     for (int e = 0; e < 2; ++e) { const int p = 2 * fq + e; const int row = row0 + (p >> 2) * 128 + (p & 3) * 16; v[e] = 1.0f / sqrtf(rss_sum(rss, row) * (1.0f / DM) + EPS); }
;     const int fr = lane & 15;
; #pragma unroll
;     for (int q = 0; q < 4; ++q) { rs[2 * q] = __shfl(v[0], fr + 16 * q); rs[2 * q + 1] = __shfl(v[1], fr + 16 * q); }
; template <class Epi>
; DI void gemm_phase(LAS unsigned char* lds, const int tid, const Gemm g, const StaticOrder& S, const Epi& E) {
;     ...
;             PG8_LDB(B0, 0, 0); PG8_LDB(B1, 0, 1); PG8_SCHED; PG8_LDA(At, 0, 0); PG8_STAGE(PG8_SA(1, 1), a1 + hstepA, voffA);
;             PG8_WAIT_V(8); PG8_WAIT_L(0); PG8_BAR; PG8_MMA(0, 0, At, B0); PG8_MMA(0, 1, At, B1); PG8_BAR; PG8_SCHED;
;             PG8_LDA(At, 0, 1); PG8_STAGE(PG8_SB(0, 0), b2, voffB); PG8_STAGE(PG8_SB(0, 1), b2 + hstepB, voffB); PG8_STAGE(PG8_SA(0, 0), a2, voffA);
;             PG8_WAIT_V(8); PG8_WAIT_L(0); PG8_BAR; PG8_MMA(1, 0, At, B0); PG8_MMA(1, 1, At, B1); PG8_BAR; PG8_SCHED;
.LBB0_667:
	s_cmp_eq_u32 s58, 2
	s_cbranch_scc0 .Lgu_rs_skip
	s_cmp_eq_u32 s101, 1
	s_cbranch_scc0 .Lgu_rs_skip
	s_waitcnt vmcnt(8)
	v_add_f32_e32 v156, v228, v229
	v_add_f32_e32 v157, v230, v231
	v_add_f32_e32 v158, v232, v233
	v_add_f32_e32 v159, v238, v239
	v_add_f32_e32 v156, v156, v157
	v_add_f32_e32 v158, v158, v159
	v_add_f32_e32 v156, v156, v158
	s_nop 1
	v_mov_b32_dpp v157, v156 quad_perm:[1,0,3,2] row_mask:0xf bank_mask:0xf
	s_nop 0
	v_add_f32_e32 v156, v156, v157
	v_fmamk_f32 v156, v156, 0x3a800000, v241
	ds_write_b32 v251, v156 offset:1024
	v_cmp_gt_f32_e32 vcc, s3, v156
	v_mul_f32_e32 v157, 0x4f800000, v156
	s_nop 1
	v_cndmask_b32_e32 v156, v156, v157, vcc
	v_sqrt_f32_e32 v157, v156
	s_nop 0
	v_add_u32_e32 v158, -1, v157
	v_fma_f32 v159, -v158, v157, v156
	v_cmp_ge_f32_e64 s[36:37], 0, v159
	v_add_u32_e32 v159, 1, v157
	s_nop 1
	v_cndmask_b32_e64 v158, v157, v158, s[36:37]
	v_fma_f32 v157, -v159, v157, v156
	v_cmp_lt_f32_e64 s[36:37], 0, v157
	s_nop 1
	v_cndmask_b32_e64 v157, v158, v159, s[36:37]
	v_mul_f32_e32 v158, 0x37800000, v157
	v_cndmask_b32_e32 v157, v157, v158, vcc
	v_cmp_class_f32_e32 vcc, v156, v242
	s_nop 1
	v_cndmask_b32_e32 v156, v157, v156, vcc
	v_div_scale_f32 v157, s[36:37], v156, v156, 1.0
	v_rcp_f32_e32 v158, v157
	s_nop 0
	v_fma_f32 v159, -v157, v158, 1.0
	v_fmac_f32_e32 v158, v159, v158
	v_div_scale_f32 v159, vcc, 1.0, v156, 1.0
	v_mul_f32_e32 v160, v159, v158
	v_fma_f32 v161, -v157, v160, v159
	v_fmac_f32_e32 v160, v161, v158
	v_fma_f32 v157, -v157, v160, v159
	s_nop 0
	v_div_fmas_f32 v157, v157, v158, v160
	v_div_fixup_f32 v156, v157, v156, 1.0
	ds_write_b32 v251, v156
.Lgu_rs_skip:
	s_add_u32 s36, s6, 0xfffc0080
	s_addc_u32 s37, s7, -1
	s_add_i32 s59, 0, 0x10000
	s_cmp_eq_u32 s58, 12
	s_cselect_b32 s41, s13, s37
	s_cselect_b32 s40, s52, s36
	v_add_u32_e32 v140, s59, v147
	s_cselect_b32 s37, s11, s57
	s_cselect_b32 s36, s53, s56
	s_add_i32 s62, 0, 0x14000
	ds_read_b128 v[156:159], v140
	ds_read_b128 v[160:163], v140 offset:1024
	ds_read_b128 v[164:167], v140 offset:2048
	ds_read_b128 v[168:171], v140 offset:3072
	v_add_u32_e32 v140, s62, v147
	ds_read_b128 v[172:175], v140
	ds_read_b128 v[176:179], v140 offset:1024
	ds_read_b128 v[180:183], v140 offset:2048
	ds_read_b128 v[184:187], v140 offset:3072
	v_lshl_add_u64 v[140:141], s[6:7], 0, v[136:137]
	s_add_i32 m0, s30, 0xc000
	ds_read_b128 v[188:191], v155
	ds_read_b128 v[192:195], v155 offset:1024
	ds_read_b128 v[196:199], v155 offset:2048
	ds_read_b128 v[208:211], v155 offset:3072
	ds_read_b128 v[212:215], v155 offset:4096
	ds_read_b128 v[216:219], v155 offset:5120
	ds_read_b128 v[220:223], v155 offset:6144
	ds_read_b128 v[224:227], v155 offset:7168
	global_load_lds_dwordx4 v[140:141], off
	v_lshl_add_u64 v[140:141], s[6:7], 0, v[138:139]
	s_add_i32 m0, s30, 0xe000
	s_nop 0
	global_load_lds_dwordx4 v[140:141], off
	s_cmp_eq_u32 s100, 0
	s_cbranch_scc1 .Lgu_ws1
	s_cmp_eq_u32 s100, 1
	s_cbranch_scc1 .Lgu_wr1
	s_waitcnt vmcnt(16)
	s_branch .Lgu_wq1
.Lgu_wr1:
	s_waitcnt vmcnt(19)
.Lgu_wq1:
	s_branch .Lgu_wd1
.Lgu_ws1:
	s_waitcnt vmcnt(8)
.Lgu_wd1:
	s_waitcnt lgkmcnt(0)
	s_barrier
	s_setprio 1
	s_waitcnt lgkmcnt(0)
	v_mfma_f32_16x16x32_bf16 v[126:129], v[156:159], v[188:191], v[126:129]
	v_mfma_f32_16x16x32_bf16 v[118:121], v[164:167], v[188:191], v[118:121]
	v_mfma_f32_16x16x32_bf16 v[110:113], v[156:159], v[196:199], v[110:113]
	v_mfma_f32_16x16x32_bf16 v[102:105], v[164:167], v[196:199], v[102:105]
	v_mfma_f32_16x16x32_bf16 v[94:97], v[156:159], v[212:215], v[94:97]
	v_mfma_f32_16x16x32_bf16 v[86:89], v[164:167], v[212:215], v[86:89]
	v_mfma_f32_16x16x32_bf16 v[78:81], v[156:159], v[220:223], v[78:81]
	v_mfma_f32_16x16x32_bf16 v[70:73], v[164:167], v[220:223], v[70:73]
	v_mfma_f32_16x16x32_bf16 v[126:129], v[160:163], v[192:195], v[126:129]
	v_mfma_f32_16x16x32_bf16 v[118:121], v[168:171], v[192:195], v[118:121]
	v_mfma_f32_16x16x32_bf16 v[110:113], v[160:163], v[208:211], v[110:113]
	v_mfma_f32_16x16x32_bf16 v[102:105], v[168:171], v[208:211], v[102:105]
	v_mfma_f32_16x16x32_bf16 v[94:97], v[160:163], v[216:219], v[94:97]
	v_mfma_f32_16x16x32_bf16 v[86:89], v[168:171], v[216:219], v[86:89]
	v_mfma_f32_16x16x32_bf16 v[78:81], v[160:163], v[224:227], v[78:81]
	v_mfma_f32_16x16x32_bf16 v[70:73], v[168:171], v[224:227], v[70:73]
	s_setprio 0
	s_setprio 1
	v_mfma_f32_16x16x32_bf16 v[122:125], v[172:175], v[188:191], v[122:125]
	v_mfma_f32_16x16x32_bf16 v[114:117], v[180:183], v[188:191], v[114:117]
	v_mfma_f32_16x16x32_bf16 v[106:109], v[172:175], v[196:199], v[106:109]
	v_mfma_f32_16x16x32_bf16 v[98:101], v[180:183], v[196:199], v[98:101]
	v_mfma_f32_16x16x32_bf16 v[90:93], v[172:175], v[212:215], v[90:93]
	v_mfma_f32_16x16x32_bf16 v[82:85], v[180:183], v[212:215], v[82:85]
	v_mfma_f32_16x16x32_bf16 v[74:77], v[172:175], v[220:223], v[74:77]
	v_mfma_f32_16x16x32_bf16 v[66:69], v[180:183], v[220:223], v[66:69]
	v_mfma_f32_16x16x32_bf16 v[122:125], v[176:179], v[192:195], v[122:125]
	v_mfma_f32_16x16x32_bf16 v[114:117], v[184:187], v[192:195], v[114:117]
	v_mfma_f32_16x16x32_bf16 v[106:109], v[176:179], v[208:211], v[106:109]
	v_mfma_f32_16x16x32_bf16 v[98:101], v[184:187], v[208:211], v[98:101]
	v_mfma_f32_16x16x32_bf16 v[90:93], v[176:179], v[216:219], v[90:93]
	v_mfma_f32_16x16x32_bf16 v[82:85], v[184:187], v[216:219], v[82:85]
	v_mfma_f32_16x16x32_bf16 v[74:77], v[176:179], v[224:227], v[74:77]
	v_mfma_f32_16x16x32_bf16 v[66:69], v[184:187], v[224:227], v[66:69]
	s_setprio 0
	s_barrier
	s_add_i32 s59, s59, s25
	v_lshl_add_u64 v[140:141], s[36:37], 0, v[0:1]
	s_mov_b32 m0, s59
	ds_read_b128 v[188:191], v155 offset:16384
	ds_read_b128 v[192:195], v155 offset:17408
	ds_read_b128 v[196:199], v155 offset:18432
	ds_read_b128 v[208:211], v155 offset:19456
	ds_read_b128 v[212:215], v155 offset:20480
	ds_read_b128 v[216:219], v155 offset:21504
	ds_read_b128 v[220:223], v155 offset:22528
	ds_read_b128 v[224:227], v155 offset:23552
	global_load_lds_dwordx4 v[140:141], off
	s_add_i32 m0, s59, 0x2000
	s_add_u32 s60, s36, 0x40000
	v_lshl_add_u64 v[148:149], s[36:37], 0, v[130:131]
	s_addc_u32 s61, s37, 0
	s_add_i32 s59, s62, s25
	global_load_lds_dwordx4 v[148:149], off
	v_lshl_add_u64 v[200:201], s[60:61], 0, v[0:1]
	s_mov_b32 m0, s59
	v_lshl_add_u64 v[202:203], s[40:41], 0, v[132:133]
	global_load_lds_dwordx4 v[200:201], off
	v_lshl_add_u64 v[200:201], s[60:61], 0, v[130:131]
	s_add_i32 m0, s59, 0x2000
	s_nop 0
	global_load_lds_dwordx4 v[200:201], off
	v_lshl_add_u64 v[200:201], s[40:41], 0, v[134:135]
	s_mov_b32 m0, s30
	s_nop 0
	global_load_lds_dwordx4 v[200:201], off
	s_mov_b32 m0, s31
	s_nop 0
	global_load_lds_dwordx4 v[202:203], off
	s_cmp_eq_u32 s100, 0
	s_cbranch_scc1 .Lgu_ws2
	s_cmp_eq_u32 s100, 1
	s_cbranch_scc1 .Lgu_wr2
	s_waitcnt vmcnt(16)
	s_branch .Lgu_wq2

; DI float rss_sum(const float* rss, int row) {
;     const f32x4* p = (const f32x4*)(rss + (size_t)row * 16); const f32x4 a = p[0], b = p[1], c = p[2], d = p[3];
;     return (((a.x + a.y) + (a.z + a.w)) + ((b.x + b.y) + (b.z + b.w))) + (((c.x + c.y) + (c.z + c.w)) + ((d.x + d.y) + (d.z + d.w))); }
; DI void row_rstd8(const float* rss, int row0, int lane, int fq, float (&rs)[8]) {
;     float v[2];
; #pragma unroll
;     for (int e = 0; e < 2; ++e) { const int p = 2 * fq + e; const int row = row0 + (p >> 2) * 128 + (p & 3) * 16; v[e] = 1.0f / sqrtf(rss_sum(rss, row) * (1.0f / DM) + EPS); }
; template <class Epi>
; DI void gemm_phase(LAS unsigned char* lds, const int tid, const Gemm g, const StaticOrder& S, const Epi& E) {
;     ...
;         const bool has_next = S.next(ui + 1, nxt);
;         const char* nA = has_next ? (const char*)g.A + (size_t)nxt.pm * tstepA : cA; const char* nB = has_next ? (const char*)g.Bt + (size_t)nxt.pn * tstepB : cB;
.LBB0_670:
	s_mov_b32 s101, 0
	s_andn2_b64 vcc, exec, s[4:5]
	s_cbranch_vccnz .Lgu_noR
	s_cmp_eq_u32 s12, s49
	s_cbranch_scc1 .Lgu_noR
	s_mov_b32 s101, 1
	v_readlane_b32 s36, v253, 49
	s_and_b32 s37, s12, 0x7f
	s_lshl_b32 s37, s37, 14
	s_nop 0
	s_add_u32 s36, s36, s37
	v_readlane_b32 s37, v253, 50
	s_nop 1
	s_addc_u32 s37, s37, 0
	s_nop 4
	global_load_dwordx4 v[228:231], v252, s[36:37]
	global_load_dwordx2 v[232:233], v252, s[36:37] offset:16
	global_load_dwordx2 v[238:239], v252, s[36:37] offset:24
